# norm1 gain/shift/scale loads hoisted; attnprep row loads issued before the rope angle computation; ctx hyena epilogue: workspace pointer derived from a live register instead of reloading, store-drain
# speedup vs baseline: 1.0948x; 1.0044x over previous
; __device__ __forceinline__ unsigned pack2(float a, float b) { unsigned r; asm("v_cvt_pk_bf16_f32 %0, %1, %2" : "=v"(r) : "v"(a), "v"(b)); return r; }
; #define layer launder_s(layer_)
; __device__ __forceinline__ void norm_item(const Params& p, int layer, int which, int item) {
;     ...
;   for (int i = 0; i < 9; i++) {
;     int row = item * 72 + wave * 9 + i;
;     const float* src = resid_src(p, layer, which, row);
;     int m = row < TL ? (row >> 11) : 8;
;     const float* md = MOD + (size_t)(layer * 9 + m) * 6144 + (which == 0 ? 0 : 3072);
;     float4 v[4];
;     float ss = 0.f;
; #pragma unroll
;     for (int q = 0; q < 4; q++) {
;       v[q] = *(const float4*)(src + q * 256 + lane * 4);
;       ss += v[q].x * v[q].x + v[q].y * v[q].y + v[q].z * v[q].z + v[q].w * v[q].w;
;     }
;     ss = wave_sum(ss);
;     float rstd = rsqrtf(ss * (1.0f / 1024.0f) + EPS);
; #pragma unroll
;     for (int q = 0; q < 4; q++) {
;       int cidx = q * 256 + lane * 4;
;       float4 gg = *(const float4*)(g + cidx);
;       float4 sh = *(const float4*)(md + cidx);
;       float4 sc = *(const float4*)(md + 1024 + cidx);
;       float o0 = v[q].x * rstd * gg.x * (1.f + sc.x) + sh.x;
;       float o1 = v[q].y * rstd * gg.y * (1.f + sc.y) + sh.y;
;       float o2 = v[q].z * rstd * gg.z * (1.f + sc.z) + sh.z;
;       float o3 = v[q].w * rstd * gg.w * (1.f + sc.w) + sh.w;
;       uint2 o; o.x = pack2(o0, o1); o.y = pack2(o2, o3);
;       *(uint2*)(XN + (size_t)row * D + cidx) = o;
;     }
;   }
.LBB0_161:
	global_load_dwordx2 v[2:3], v[2:3], off
	v_lshlrev_b64 v[0:1], 12, v[0:1]
	v_min_i32_e32 v9, 0x4000, v18
	v_ashrrev_i32_e32 v9, 11, v9
	v_add_u32_e32 v9, s19, v9
	s_movk_i32 s4, 0x6000
	v_mad_i64_i32 v[46:47], s[4:5], v9, s4, v[12:13]
	s_mov_b64 s[4:5], 0x1000
	s_nop 0
	v_lshl_add_u64 v[50:51], v[46:47], 0, s[4:5]
	v_lshl_add_u64 v[38:39], v[50:51], 0, v[4:5]
	v_lshl_add_u64 v[120:121], v[50:51], 0, v[4:5]
	v_lshl_add_u64 v[52:53], v[46:47], 0, v[4:5]
	v_lshlrev_b64 v[18:19], 11, v[18:19]
	v_lshl_add_u64 v[18:19], v[16:17], 0, v[18:19]
	s_add_i32 s18, s18, 1
	s_cmp_lg_u32 s18, 9
	s_waitcnt vmcnt(0) lgkmcnt(0)
	v_lshl_add_u64 v[0:1], v[2:3], 0, v[0:1]
	v_lshl_add_u64 v[0:1], v[0:1], 0, v[4:5]
	global_load_dwordx4 v[26:29], v[0:1], off
	global_load_dwordx4 v[30:33], v[0:1], off offset:1024
	global_load_dwordx4 v[34:37], v[0:1], off offset:2048
	s_nop 0
	global_load_dwordx4 v[0:3], v[0:1], off offset:3072
	s_nop 0
	global_load_dwordx4 v[38:41], v[38:39], off
	s_nop 0
	global_load_dwordx4 v[42:45], v[14:15], off
	global_load_dwordx4 v[46:49], v[52:53], off
	global_load_dwordx4 v[84:87], v[14:15], off offset:1024
	global_load_dwordx4 v[88:91], v[120:121], off offset:1024
	global_load_dwordx4 v[92:95], v[52:53], off offset:1024
	global_load_dwordx4 v[96:99], v[14:15], off offset:2048
	global_load_dwordx4 v[100:103], v[120:121], off offset:2048
	global_load_dwordx4 v[104:107], v[52:53], off offset:2048
	global_load_dwordx4 v[108:111], v[14:15], off offset:3072
	global_load_dwordx4 v[112:115], v[120:121], off offset:3072
	global_load_dwordx4 v[116:119], v[52:53], off offset:3072
	s_waitcnt vmcnt(0) lgkmcnt(0)
	v_mov_b32_e32 v56, v27
	v_mov_b32_e32 v57, v31
	v_mov_b32_e32 v54, v26
	v_mov_b32_e32 v55, v30
	v_mov_b32_e32 v64, v35
	v_mov_b32_e32 v65, v1
	v_pk_mul_f32 v[56:57], v[56:57], v[56:57]
	v_mov_b32_e32 v58, v28
	v_mov_b32_e32 v59, v32
	v_mov_b32_e32 v62, v34
	v_mov_b32_e32 v63, v0
	v_pk_mul_f32 v[64:65], v[64:65], v[64:65]
	v_pk_fma_f32 v[54:55], v[54:55], v[54:55], v[56:57]
	v_mov_b32_e32 v60, v29
	v_mov_b32_e32 v61, v33
	v_mov_b32_e32 v66, v36
	v_mov_b32_e32 v67, v2
	v_pk_fma_f32 v[56:57], v[62:63], v[62:63], v[64:65]
	v_pk_fma_f32 v[54:55], v[58:59], v[58:59], v[54:55]
	v_mov_b32_e32 v68, v37
	v_mov_b32_e32 v69, v3
	v_pk_fma_f32 v[56:57], v[66:67], v[66:67], v[56:57]
	v_pk_fma_f32 v[54:55], v[60:61], v[60:61], v[54:55]
	v_pk_fma_f32 v[56:57], v[68:69], v[68:69], v[56:57]
	v_add_f32_e32 v9, v54, v55
	v_add_f32_e32 v9, v9, v56
	v_add_f32_e32 v9, v9, v57
	ds_bpermute_b32 v54, v20, v9
	v_add_f32_e32 v38, 1.0, v38
	v_add_f32_e32 v39, 1.0, v39
	v_add_f32_e32 v40, 1.0, v40
	v_add_f32_e32 v41, 1.0, v41
	s_waitcnt lgkmcnt(0)
	v_add_f32_e32 v9, v9, v54
	ds_bpermute_b32 v54, v21, v9
	s_waitcnt lgkmcnt(0)
	v_add_f32_e32 v9, v9, v54
	ds_bpermute_b32 v54, v22, v9
	s_waitcnt lgkmcnt(0)
	v_add_f32_e32 v9, v9, v54
	ds_bpermute_b32 v54, v23, v9
	s_waitcnt lgkmcnt(0)
	v_add_f32_e32 v9, v9, v54
	ds_bpermute_b32 v54, v24, v9
	s_waitcnt lgkmcnt(0)
	v_add_f32_e32 v9, v9, v54
	ds_bpermute_b32 v56, v25, v9
	v_lshl_add_u64 v[54:55], v[50:51], 0, v[160:161]
	s_waitcnt lgkmcnt(0)
	v_add_f32_e32 v9, v9, v56
	v_fmamk_f32 v9, v9, 0x3a800000, v229
	v_mul_f32_e32 v56, 0x4b800000, v9
	v_cmp_gt_f32_e32 vcc, s89, v9
	s_nop 1
	v_cndmask_b32_e32 v9, v9, v56, vcc
	v_rsq_f32_e32 v9, v9
	s_nop 0
	v_mul_f32_e32 v56, 0x45800000, v9
	v_cndmask_b32_e32 v9, v9, v56, vcc
	v_mul_f32_e32 v26, v26, v9
	v_mul_f32_e32 v27, v27, v9
	v_mul_f32_e32 v28, v28, v9
	v_mul_f32_e32 v29, v29, v9
	v_mul_f32_e32 v26, v42, v26
	v_mul_f32_e32 v27, v43, v27
	v_mul_f32_e32 v28, v44, v28
	v_mul_f32_e32 v29, v45, v29
	v_fma_f32 v26, v38, v26, v46
	v_fma_f32 v27, v39, v27, v47
	v_fma_f32 v28, v40, v28, v48
	v_fmac_f32_e32 v49, v29, v41
	v_cvt_pk_bf16_f32 v26, v26, v27
	v_cvt_pk_bf16_f32 v27, v28, v49
	global_store_dwordx2 v[18:19], v[26:27], off
	v_mov_b32_e32 v26, v84
	v_mov_b32_e32 v27, v85
	v_mov_b32_e32 v28, v86
	v_mov_b32_e32 v29, v87
	s_nop 0
	v_mov_b32_e32 v38, v88
	v_mov_b32_e32 v39, v89
	v_mov_b32_e32 v40, v90
	v_mov_b32_e32 v41, v91
	v_mov_b32_e32 v42, v92
	v_mov_b32_e32 v43, v93
	v_mov_b32_e32 v44, v94
	v_mov_b32_e32 v45, v95
	v_mul_f32_e32 v30, v30, v9
	v_mul_f32_e32 v31, v31, v9
	v_mul_f32_e32 v32, v32, v9
	v_mul_f32_e32 v33, v33, v9
	v_lshl_add_u64 v[46:47], v[50:51], 0, v[6:7]
	v_mul_f32_e32 v34, v34, v9
	v_mul_f32_e32 v35, v35, v9
	v_mul_f32_e32 v36, v36, v9
	v_mul_f32_e32 v37, v37, v9
	v_mul_f32_e32 v0, v0, v9
	v_mul_f32_e32 v1, v1, v9
	v_mul_f32_e32 v2, v2, v9
	v_mul_f32_e32 v3, v3, v9
	s_waitcnt lgkmcnt(0)
	v_mul_f32_e32 v26, v30, v26
	v_add_f32_e32 v30, 1.0, v38
	v_mul_f32_e32 v27, v31, v27
	v_add_f32_e32 v31, 1.0, v39
	v_mul_f32_e32 v28, v32, v28
	v_add_f32_e32 v32, 1.0, v40
	v_mul_f32_e32 v29, v33, v29
	v_add_f32_e32 v33, 1.0, v41
	v_fma_f32 v26, v26, v30, v42
	v_fma_f32 v27, v27, v31, v43
	v_fma_f32 v28, v28, v32, v44
	v_fmac_f32_e32 v45, v29, v33
	v_cvt_pk_bf16_f32 v26, v26, v27
	v_cvt_pk_bf16_f32 v27, v28, v45
	global_store_dwordx2 v[18:19], v[26:27], off offset:512
	v_mov_b32_e32 v26, v96
	v_mov_b32_e32 v27, v97
	v_mov_b32_e32 v28, v98
	v_mov_b32_e32 v29, v99
	s_nop 0
	v_mov_b32_e32 v30, v100
	v_mov_b32_e32 v31, v101
	v_mov_b32_e32 v32, v102
	v_mov_b32_e32 v33, v103
	v_mov_b32_e32 v38, v104
	v_mov_b32_e32 v39, v105
	v_mov_b32_e32 v40, v106
	v_mov_b32_e32 v41, v107
	v_lshl_add_u64 v[42:43], v[50:51], 0, v[10:11]
	s_waitcnt lgkmcnt(0)
	v_mul_f32_e32 v26, v34, v26
	v_add_f32_e32 v30, 1.0, v30
	v_mul_f32_e32 v27, v35, v27
	v_add_f32_e32 v31, 1.0, v31
	v_mul_f32_e32 v28, v36, v28
	v_add_f32_e32 v32, 1.0, v32
	v_mul_f32_e32 v29, v37, v29
	v_add_f32_e32 v33, 1.0, v33
	v_fma_f32 v26, v26, v30, v38
	v_fma_f32 v27, v27, v31, v39
	v_fma_f32 v28, v28, v32, v40
	v_fmac_f32_e32 v41, v29, v33
	v_cvt_pk_bf16_f32 v26, v26, v27
	v_cvt_pk_bf16_f32 v27, v28, v41
	global_store_dwordx2 v[18:19], v[26:27], off offset:1024
	v_mov_b32_e32 v26, v108
	v_mov_b32_e32 v27, v109
	v_mov_b32_e32 v28, v110
	v_mov_b32_e32 v29, v111
	s_nop 0
	v_mov_b32_e32 v30, v112
	v_mov_b32_e32 v31, v113
	v_mov_b32_e32 v32, v114
	v_mov_b32_e32 v33, v115
	v_mov_b32_e32 v34, v116
	v_mov_b32_e32 v35, v117
	v_mov_b32_e32 v36, v118
	v_mov_b32_e32 v37, v119
	s_waitcnt lgkmcnt(0)
	v_mul_f32_e32 v0, v0, v26
	v_add_f32_e32 v9, 1.0, v30
	v_mul_f32_e32 v1, v1, v27
	v_add_f32_e32 v26, 1.0, v31
	v_mul_f32_e32 v2, v2, v28
	v_add_f32_e32 v27, 1.0, v32
	v_mul_f32_e32 v3, v3, v29
	v_add_f32_e32 v28, 1.0, v33
	v_fma_f32 v0, v0, v9, v34
	v_fma_f32 v1, v1, v26, v35
	v_fma_f32 v2, v2, v27, v36
	v_fmac_f32_e32 v37, v3, v28
	v_cvt_pk_bf16_f32 v0, v0, v1
	v_cvt_pk_bf16_f32 v1, v2, v37
	global_store_dwordx2 v[18:19], v[0:1], off offset:1536
	s_cbranch_scc0 .LBB0_158

; __device__ __forceinline__ u16 f2bf(float f) { unsigned r; asm("v_cvt_pk_bf16_f32 %0, %1, %1" : "=v"(r) : "v"(f)); return (u16)r; }
; __device__ __forceinline__ float bf2f(u16 h) { return __uint_as_float(((unsigned)h) << 16); }
; __device__ __forceinline__ void attnprep_item(const Params& p, int layer, int item) {
;     ...
;   for (int i = 0; i < 9; i++) {
;     int row = item * 72 + wave * 9 + i;
;     bool lat = row < TL;
;     float sn = 0.f, cs = 1.f;
;     if (lat) {
;       int t = row & 2047;
;       float pos = (jj < 16) ? (float)(t >> 6) : (float)(t & 63);
;       sincosf(pos * inv, &sn, &cs);
;     }
;     for (int h = 0; h < 10; h++) {
;       float v = bf2f(ZA[(size_t)row * 1280 + 512 + h * 64 + lane]);
;       float ss = wave_sum(v * v);
;       float nv = v * rsqrtf(ss * (1.0f / 64.0f) + EPS) * (h < 8 ? qg : kg);
;       float pv = __shfl_xor(nv, 1);
;       float o = (lane & 1) ? (pv * sn + nv * cs) : (nv * cs - pv * sn);
;       if (h < 8) QR[(size_t)row * 512 + h * 64 + lane] = f2bf(o);
.LBB0_424:
	s_or_b64 exec, exec, s[16:17]
	v_ashrrev_i32_e32 v15, 31, v14
	v_lshlrev_b64 v[12:13], 8, v[14:15]
	v_lshlrev_b64 v[14:15], 10, v[14:15]
	v_lshl_add_u64 v[14:15], v[6:7], 0, v[14:15]
	v_lshl_add_u64 v[12:13], v[2:3], 0, v[12:13]
	v_lshl_add_u64 v[12:13], v[12:13], 0, v[160:161]
	s_mov_b32 s8, 0x1ca0c000
	v_add_co_u32_e64 v12, s[8:9], s8, v12
	s_nop 1
	v_addc_co_u32_e64 v13, s[8:9], 0, v13, s[8:9]
	s_add_i32 s20, s20, 1
	s_cmp_lg_u32 s20, 9
	s_waitcnt vmcnt(0) lgkmcnt(0)
	v_lshlrev_b32_e32 v40, 16, v40
	v_lshlrev_b32_e32 v41, 16, v41
	v_lshlrev_b32_e32 v42, 16, v42
	v_lshlrev_b32_e32 v43, 16, v43
	v_lshlrev_b32_e32 v44, 16, v44
	v_lshlrev_b32_e32 v45, 16, v45
	v_lshlrev_b32_e32 v46, 16, v46
	v_lshlrev_b32_e32 v47, 16, v47
	v_lshlrev_b32_e32 v48, 16, v48
	v_lshlrev_b32_e32 v49, 16, v49
	v_mul_f32_e32 v50, v40, v40
	v_mul_f32_e32 v51, v41, v41
	v_mul_f32_e32 v52, v42, v42
	v_mul_f32_e32 v53, v43, v43
	v_mul_f32_e32 v54, v44, v44
	v_mul_f32_e32 v55, v45, v45
	v_mul_f32_e32 v56, v46, v46
	v_mul_f32_e32 v57, v47, v47
	v_mul_f32_e32 v58, v48, v48
	v_mul_f32_e32 v59, v49, v49
	ds_bpermute_b32 v50, v19, v50
	ds_bpermute_b32 v51, v19, v51
	ds_bpermute_b32 v52, v19, v52
	ds_bpermute_b32 v53, v19, v53
	ds_bpermute_b32 v54, v19, v54
	ds_bpermute_b32 v55, v19, v55
	ds_bpermute_b32 v56, v19, v56
	ds_bpermute_b32 v57, v19, v57
	ds_bpermute_b32 v58, v19, v58
	ds_bpermute_b32 v59, v19, v59
	s_waitcnt lgkmcnt(0)
	v_fmac_f32_e32 v50, v40, v40
	v_fmac_f32_e32 v51, v41, v41
	v_fmac_f32_e32 v52, v42, v42
	v_fmac_f32_e32 v53, v43, v43
	v_fmac_f32_e32 v54, v44, v44
	v_fmac_f32_e32 v55, v45, v45
	v_fmac_f32_e32 v56, v46, v46
	v_fmac_f32_e32 v57, v47, v47
	v_fmac_f32_e32 v58, v48, v48
	v_fmac_f32_e32 v59, v49, v49
	ds_bpermute_b32 v60, v20, v50
	ds_bpermute_b32 v61, v20, v51
	ds_bpermute_b32 v62, v20, v52
	ds_bpermute_b32 v63, v20, v53
	ds_bpermute_b32 v64, v20, v54
	ds_bpermute_b32 v65, v20, v55
	ds_bpermute_b32 v66, v20, v56
	ds_bpermute_b32 v67, v20, v57
	ds_bpermute_b32 v68, v20, v58
	ds_bpermute_b32 v69, v20, v59
	s_waitcnt lgkmcnt(0)
	v_add_f32_e32 v50, v50, v60
	v_add_f32_e32 v51, v51, v61
	v_add_f32_e32 v52, v52, v62
	v_add_f32_e32 v53, v53, v63
	v_add_f32_e32 v54, v54, v64
	v_add_f32_e32 v55, v55, v65
	v_add_f32_e32 v56, v56, v66
	v_add_f32_e32 v57, v57, v67
	v_add_f32_e32 v58, v58, v68
	v_add_f32_e32 v59, v59, v69
	ds_bpermute_b32 v60, v21, v50
	ds_bpermute_b32 v61, v21, v51
	ds_bpermute_b32 v62, v21, v52
	ds_bpermute_b32 v63, v21, v53
	ds_bpermute_b32 v64, v21, v54
	ds_bpermute_b32 v65, v21, v55
	ds_bpermute_b32 v66, v21, v56
	ds_bpermute_b32 v67, v21, v57
	ds_bpermute_b32 v68, v21, v58
	ds_bpermute_b32 v69, v21, v59
	s_waitcnt lgkmcnt(0)
	v_add_f32_e32 v50, v50, v60
	v_add_f32_e32 v51, v51, v61
	v_add_f32_e32 v52, v52, v62
	v_add_f32_e32 v53, v53, v63
	v_add_f32_e32 v54, v54, v64
	v_add_f32_e32 v55, v55, v65
	v_add_f32_e32 v56, v56, v66
	v_add_f32_e32 v57, v57, v67
	v_add_f32_e32 v58, v58, v68
	v_add_f32_e32 v59, v59, v69
	ds_bpermute_b32 v60, v22, v50
	ds_bpermute_b32 v61, v22, v51
	ds_bpermute_b32 v62, v22, v52
	ds_bpermute_b32 v63, v22, v53
	ds_bpermute_b32 v64, v22, v54
	ds_bpermute_b32 v65, v22, v55
	ds_bpermute_b32 v66, v22, v56
	ds_bpermute_b32 v67, v22, v57
	ds_bpermute_b32 v68, v22, v58
	ds_bpermute_b32 v69, v22, v59
	s_waitcnt lgkmcnt(0)
	v_add_f32_e32 v50, v50, v60
	v_add_f32_e32 v51, v51, v61
	v_add_f32_e32 v52, v52, v62
	v_add_f32_e32 v53, v53, v63
	v_add_f32_e32 v54, v54, v64
	v_add_f32_e32 v55, v55, v65
	v_add_f32_e32 v56, v56, v66
	v_add_f32_e32 v57, v57, v67
	v_add_f32_e32 v58, v58, v68
	v_add_f32_e32 v59, v59, v69
	ds_bpermute_b32 v60, v23, v50
	ds_bpermute_b32 v61, v23, v51
	ds_bpermute_b32 v62, v23, v52
	ds_bpermute_b32 v63, v23, v53
	ds_bpermute_b32 v64, v23, v54
	ds_bpermute_b32 v65, v23, v55
	ds_bpermute_b32 v66, v23, v56
	ds_bpermute_b32 v67, v23, v57
	ds_bpermute_b32 v68, v23, v58
	ds_bpermute_b32 v69, v23, v59
	s_waitcnt lgkmcnt(0)
	v_add_f32_e32 v50, v50, v60
	v_add_f32_e32 v51, v51, v61
	v_add_f32_e32 v52, v52, v62
	v_add_f32_e32 v53, v53, v63
	v_add_f32_e32 v54, v54, v64
	v_add_f32_e32 v55, v55, v65
	v_add_f32_e32 v56, v56, v66
	v_add_f32_e32 v57, v57, v67
	v_add_f32_e32 v58, v58, v68
	v_add_f32_e32 v59, v59, v69
	ds_bpermute_b32 v60, v24, v50
	ds_bpermute_b32 v61, v24, v51
	ds_bpermute_b32 v62, v24, v52
	ds_bpermute_b32 v63, v24, v53
	ds_bpermute_b32 v64, v24, v54
	ds_bpermute_b32 v65, v24, v55
	ds_bpermute_b32 v66, v24, v56
	ds_bpermute_b32 v67, v24, v57
	ds_bpermute_b32 v68, v24, v58
	ds_bpermute_b32 v69, v24, v59
	s_waitcnt lgkmcnt(0)
; __device__ __forceinline__ u16 f2bf(float f) { unsigned r; asm("v_cvt_pk_bf16_f32 %0, %1, %1" : "=v"(r) : "v"(f)); return (u16)r; }
; __device__ __forceinline__ void attnprep_item(const Params& p, int layer, int item) {
;     ...
;       float ss = wave_sum(v * v);
;       float nv = v * rsqrtf(ss * (1.0f / 64.0f) + EPS) * (h < 8 ? qg : kg);
;       float pv = __shfl_xor(nv, 1);
;       float o = (lane & 1) ? (pv * sn + nv * cs) : (nv * cs - pv * sn);
;       if (h < 8) QR[(size_t)row * 512 + h * 64 + lane] = f2bf(o);
;       else KR[(size_t)row * 128 + (h - 8) * 64 + lane] = f2bf(o);
;     }
	v_add_f32_e32 v50, v50, v60
	v_add_f32_e32 v51, v51, v61
	v_add_f32_e32 v52, v52, v62
	v_add_f32_e32 v53, v53, v63
	v_add_f32_e32 v54, v54, v64
	v_add_f32_e32 v55, v55, v65
	v_add_f32_e32 v56, v56, v66
	v_add_f32_e32 v57, v57, v67
	v_add_f32_e32 v58, v58, v68
	v_add_f32_e32 v59, v59, v69
	v_fmamk_f32 v50, v50, 0x3c800000, v229
	v_fmamk_f32 v51, v51, 0x3c800000, v229
	v_fmamk_f32 v52, v52, 0x3c800000, v229
	v_fmamk_f32 v53, v53, 0x3c800000, v229
	v_fmamk_f32 v54, v54, 0x3c800000, v229
	v_fmamk_f32 v55, v55, 0x3c800000, v229
	v_fmamk_f32 v56, v56, 0x3c800000, v229
	v_fmamk_f32 v57, v57, 0x3c800000, v229
	v_fmamk_f32 v58, v58, 0x3c800000, v229
	v_fmamk_f32 v59, v59, 0x3c800000, v229
	v_cmp_gt_f32_e64 s[8:9], s89, v50
	v_mul_f32_e32 v60, 0x4b800000, v50
	s_nop 0
	v_cndmask_b32_e64 v50, v50, v60, s[8:9]
	v_rsq_f32_e32 v50, v50
	s_nop 0
	v_mul_f32_e32 v60, 0x45800000, v50
	v_cndmask_b32_e64 v50, v50, v60, s[8:9]
	v_mul_f32_e32 v40, v50, v40
	v_mul_f32_e32 v40, v16, v40
	v_cmp_gt_f32_e64 s[8:9], s89, v51
	v_mul_f32_e32 v61, 0x4b800000, v51
	s_nop 0
	v_cndmask_b32_e64 v51, v51, v61, s[8:9]
	v_rsq_f32_e32 v51, v51
	s_nop 0
	v_mul_f32_e32 v61, 0x45800000, v51
	v_cndmask_b32_e64 v51, v51, v61, s[8:9]
	v_mul_f32_e32 v41, v51, v41
	v_mul_f32_e32 v41, v16, v41
	v_cmp_gt_f32_e64 s[8:9], s89, v52
	v_mul_f32_e32 v62, 0x4b800000, v52
	s_nop 0
	v_cndmask_b32_e64 v52, v52, v62, s[8:9]
	v_rsq_f32_e32 v52, v52
	s_nop 0
	v_mul_f32_e32 v62, 0x45800000, v52
	v_cndmask_b32_e64 v52, v52, v62, s[8:9]
	v_mul_f32_e32 v42, v52, v42
	v_mul_f32_e32 v42, v16, v42
	v_cmp_gt_f32_e64 s[8:9], s89, v53
	v_mul_f32_e32 v63, 0x4b800000, v53
	s_nop 0
	v_cndmask_b32_e64 v53, v53, v63, s[8:9]
	v_rsq_f32_e32 v53, v53
	s_nop 0
	v_mul_f32_e32 v63, 0x45800000, v53
	v_cndmask_b32_e64 v53, v53, v63, s[8:9]
	v_mul_f32_e32 v43, v53, v43
	v_mul_f32_e32 v43, v16, v43
	v_cmp_gt_f32_e64 s[8:9], s89, v54
	v_mul_f32_e32 v64, 0x4b800000, v54
	s_nop 0
	v_cndmask_b32_e64 v54, v54, v64, s[8:9]
	v_rsq_f32_e32 v54, v54
	s_nop 0
	v_mul_f32_e32 v64, 0x45800000, v54
	v_cndmask_b32_e64 v54, v54, v64, s[8:9]
	v_mul_f32_e32 v44, v54, v44
	v_mul_f32_e32 v44, v16, v44
	v_cmp_gt_f32_e64 s[8:9], s89, v55
	v_mul_f32_e32 v65, 0x4b800000, v55
	s_nop 0
	v_cndmask_b32_e64 v55, v55, v65, s[8:9]
	v_rsq_f32_e32 v55, v55
	s_nop 0
	v_mul_f32_e32 v65, 0x45800000, v55
	v_cndmask_b32_e64 v55, v55, v65, s[8:9]
	v_mul_f32_e32 v45, v55, v45
	v_mul_f32_e32 v45, v16, v45
	v_cmp_gt_f32_e64 s[8:9], s89, v56
	v_mul_f32_e32 v66, 0x4b800000, v56
	s_nop 0
	v_cndmask_b32_e64 v56, v56, v66, s[8:9]
	v_rsq_f32_e32 v56, v56
	s_nop 0
	v_mul_f32_e32 v66, 0x45800000, v56
	v_cndmask_b32_e64 v56, v56, v66, s[8:9]
	v_mul_f32_e32 v46, v56, v46
	v_mul_f32_e32 v46, v16, v46
	v_cmp_gt_f32_e64 s[8:9], s89, v57
	v_mul_f32_e32 v67, 0x4b800000, v57
	s_nop 0
	v_cndmask_b32_e64 v57, v57, v67, s[8:9]
	v_rsq_f32_e32 v57, v57
	s_nop 0
	v_mul_f32_e32 v67, 0x45800000, v57
	v_cndmask_b32_e64 v57, v57, v67, s[8:9]
	v_mul_f32_e32 v47, v57, v47
	v_mul_f32_e32 v47, v16, v47
	v_cmp_gt_f32_e64 s[8:9], s89, v58
	v_mul_f32_e32 v68, 0x4b800000, v58
	s_nop 0
	v_cndmask_b32_e64 v58, v58, v68, s[8:9]
	v_rsq_f32_e32 v58, v58
	s_nop 0
	v_mul_f32_e32 v68, 0x45800000, v58
	v_cndmask_b32_e64 v58, v58, v68, s[8:9]
	v_mul_f32_e32 v48, v58, v48
	v_mul_f32_e32 v48, v17, v48
	v_cmp_gt_f32_e64 s[8:9], s89, v59
	v_mul_f32_e32 v69, 0x4b800000, v59
	s_nop 0
	v_cndmask_b32_e64 v59, v59, v69, s[8:9]
	v_rsq_f32_e32 v59, v59
	s_nop 0
	v_mul_f32_e32 v69, 0x45800000, v59
	v_cndmask_b32_e64 v59, v59, v69, s[8:9]
	v_mul_f32_e32 v49, v59, v49
	v_mul_f32_e32 v49, v17, v49
	ds_bpermute_b32 v60, v24, v40
	ds_bpermute_b32 v61, v24, v41
	ds_bpermute_b32 v62, v24, v42
	ds_bpermute_b32 v63, v24, v43
	ds_bpermute_b32 v64, v24, v44
	ds_bpermute_b32 v65, v24, v45
	ds_bpermute_b32 v66, v24, v46
	ds_bpermute_b32 v67, v24, v47
	ds_bpermute_b32 v68, v24, v48
	ds_bpermute_b32 v69, v24, v49
	s_waitcnt lgkmcnt(0)
	v_mul_f32_e32 v60, v25, v60
	v_cndmask_b32_e64 v60, v60, -v60, vcc
	v_fmac_f32_e32 v60, v9, v40
	v_cvt_pk_bf16_f32 v40, v60, v60
	v_mul_f32_e32 v61, v25, v61
	v_cndmask_b32_e64 v61, v61, -v61, vcc
	v_fmac_f32_e32 v61, v9, v41
	v_cvt_pk_bf16_f32 v41, v61, v61
	v_mul_f32_e32 v62, v25, v62
	v_cndmask_b32_e64 v62, v62, -v62, vcc
	v_fmac_f32_e32 v62, v9, v42
	v_cvt_pk_bf16_f32 v42, v62, v62
	v_mul_f32_e32 v63, v25, v63
	v_cndmask_b32_e64 v63, v63, -v63, vcc
	v_fmac_f32_e32 v63, v9, v43
	v_cvt_pk_bf16_f32 v43, v63, v63
	v_mul_f32_e32 v64, v25, v64
	v_cndmask_b32_e64 v64, v64, -v64, vcc
	v_fmac_f32_e32 v64, v9, v44
	v_cvt_pk_bf16_f32 v44, v64, v64
	v_mul_f32_e32 v65, v25, v65
	v_cndmask_b32_e64 v65, v65, -v65, vcc
	v_fmac_f32_e32 v65, v9, v45
	v_cvt_pk_bf16_f32 v45, v65, v65
	v_mul_f32_e32 v66, v25, v66
	v_cndmask_b32_e64 v66, v66, -v66, vcc
	v_fmac_f32_e32 v66, v9, v46
	v_cvt_pk_bf16_f32 v46, v66, v66
	v_mul_f32_e32 v67, v25, v67
	v_cndmask_b32_e64 v67, v67, -v67, vcc
	v_fmac_f32_e32 v67, v9, v47
	v_cvt_pk_bf16_f32 v47, v67, v67
	v_mul_f32_e32 v68, v25, v68
	v_cndmask_b32_e64 v68, v68, -v68, vcc
	v_fmac_f32_e32 v68, v9, v48
	v_cvt_pk_bf16_f32 v48, v68, v68
	v_mul_f32_e32 v69, v25, v69
	v_cndmask_b32_e64 v69, v69, -v69, vcc
	v_fmac_f32_e32 v69, v9, v49
	v_cvt_pk_bf16_f32 v49, v69, v69
	global_store_short v[14:15], v40, off
	global_store_short v[14:15], v41, off offset:128
	global_store_short v[14:15], v42, off offset:256
	global_store_short v[14:15], v43, off offset:384
	global_store_short v[14:15], v44, off offset:512
	global_store_short v[14:15], v45, off offset:640
	global_store_short v[14:15], v46, off offset:768
	global_store_short v[14:15], v47, off offset:896
	global_store_short v[12:13], v48, off
	global_store_short v[12:13], v49, off offset:128
	s_cbranch_scc0 .LBB0_421
; __device__ __forceinline__ void attnprep_item(const Params& p, int layer, int item) {
;     ...
;   for (int i = 0; i < 9; i++) {
;     int row = item * 72 + wave * 9 + i;
;     bool lat = row < TL;
;     float sn = 0.f, cs = 1.f;
;     if (lat) {
;       int t = row & 2047;
;       float pos = (jj < 16) ? (float)(t >> 6) : (float)(t & 63);
;       sincosf(pos * inv, &sn, &cs);
.LBB0_425:
	v_add_u32_e32 v14, s20, v8
	s_movk_i32 s10, 0xa00
	v_mad_i64_i32 v[10:11], s[10:11], v14, s10, v[4:5]
	global_load_ushort v40, v[10:11], off
	global_load_ushort v41, v[10:11], off offset:128
	global_load_ushort v42, v[10:11], off offset:256
	global_load_ushort v43, v[10:11], off offset:384
	global_load_ushort v44, v[10:11], off offset:512
	global_load_ushort v45, v[10:11], off offset:640
	global_load_ushort v46, v[10:11], off offset:768
	global_load_ushort v47, v[10:11], off offset:896
	global_load_ushort v48, v[10:11], off offset:1024
	global_load_ushort v49, v[10:11], off offset:1152
	s_movk_i32 s8, 0x4000
	v_cmp_gt_i32_e64 s[8:9], s8, v14
	v_mov_b32_e32 v25, 0
	v_mov_b32_e32 v9, 1.0
	s_and_saveexec_b64 s[16:17], s[8:9]
	s_cbranch_execz .LBB0_424
	v_bfe_u32 v9, v14, 6, 5
	v_and_b32_e32 v10, 63, v14
	v_cndmask_b32_e64 v9, v10, v9, s[6:7]
	v_cvt_f32_ubyte0_e32 v9, v9
	v_mul_f32_e32 v9, v18, v9
	s_brev_b32 s8, 18
	v_and_b32_e32 v10, 0x7fffffff, v9
	v_cmp_nlt_f32_e64 s[8:9], |v9|, s8
	s_and_saveexec_b64 s[10:11], s[8:9]
	s_xor_b64 s[18:19], exec, s[10:11]
	s_cbranch_execz .LBB0_428
	v_lshrrev_b32_e32 v11, 23, v10
	v_add_u32_e32 v11, 0xffffff88, v11
	v_cmp_lt_u32_e64 s[8:9], 63, v11
	s_mov_b32 s14, 0xfe5163ab
	v_mov_b32_e32 v27, v161
	v_cndmask_b32_e64 v12, 0, v243, s[8:9]
	v_add_u32_e32 v11, v12, v11
	v_cmp_lt_u32_e64 s[10:11], 31, v11
	v_mov_b32_e32 v29, v161
	v_mov_b32_e32 v31, v161
	v_cndmask_b32_e64 v12, 0, v244, s[10:11]
	v_add_u32_e32 v11, v12, v11
	v_cmp_lt_u32_e64 s[12:13], 31, v11
	v_mov_b32_e32 v33, v161
	v_mov_b32_e32 v35, v161
	v_cndmask_b32_e64 v12, 0, v244, s[12:13]
	v_add_u32_e32 v11, v12, v11
	v_and_b32_e32 v12, 0x7fffff, v10
	v_or_b32_e32 v15, 0x800000, v12
	v_mad_u64_u32 v[12:13], s[14:15], v15, s14, 0
	v_mov_b32_e32 v26, v13
	s_mov_b32 s14, 0x3c439041
	v_mad_u64_u32 v[26:27], s[14:15], v15, s14, v[26:27]
	v_mov_b32_e32 v28, v27
	s_mov_b32 s14, 0xdb629599
	v_mad_u64_u32 v[28:29], s[14:15], v15, s14, v[28:29]
	v_mov_b32_e32 v30, v29
	s_mov_b32 s14, 0xf534ddc0
	v_mad_u64_u32 v[30:31], s[14:15], v15, s14, v[30:31]
	v_mov_b32_e32 v32, v31
	s_mov_b32 s14, 0xfc2757d1
	v_mad_u64_u32 v[32:33], s[14:15], v15, s14, v[32:33]
	v_mov_b32_e32 v34, v33
	s_mov_b32 s14, 0x4e441529
	v_mad_u64_u32 v[34:35], s[14:15], v15, s14, v[34:35]
	v_mov_b32_e32 v36, v35
	v_mov_b32_e32 v37, v161
	s_mov_b32 s14, 0xa2f9836e
	v_mad_u64_u32 v[36:37], s[14:15], v15, s14, v[36:37]
	v_cndmask_b32_e64 v13, v34, v30, s[8:9]
	v_cndmask_b32_e64 v15, v36, v32, s[8:9]
	v_cndmask_b32_e64 v27, v37, v34, s[8:9]
	v_cndmask_b32_e64 v25, v15, v13, s[10:11]
	v_cndmask_b32_e64 v15, v27, v15, s[10:11]
	v_cndmask_b32_e64 v27, v32, v28, s[8:9]
	v_cndmask_b32_e64 v13, v13, v27, s[10:11]
	v_sub_u32_e32 v29, 32, v11
	v_cmp_eq_u32_e64 s[14:15], 0, v11
	v_cndmask_b32_e64 v11, v30, v26, s[8:9]
	v_cndmask_b32_e64 v15, v15, v25, s[12:13]
	v_cndmask_b32_e64 v25, v25, v13, s[12:13]
	v_cndmask_b32_e64 v26, v27, v11, s[10:11]
	v_alignbit_b32 v31, v15, v25, v29
	v_cndmask_b32_e64 v13, v13, v26, s[12:13]
	v_cndmask_b32_e64 v12, v28, v12, s[8:9]
	v_cndmask_b32_e64 v15, v31, v15, s[14:15]
	v_alignbit_b32 v27, v25, v13, v29
	v_cndmask_b32_e64 v11, v11, v12, s[10:11]
	v_cndmask_b32_e64 v25, v27, v25, s[14:15]
	v_bfe_u32 v31, v15, 29, 1
	v_cndmask_b32_e64 v11, v26, v11, s[12:13]
	v_alignbit_b32 v27, v15, v25, 30
	v_sub_u32_e32 v32, 0, v31
	v_alignbit_b32 v12, v13, v11, v29
	v_xor_b32_e32 v27, v27, v32
	v_cndmask_b32_e64 v12, v12, v13, s[14:15]
	v_alignbit_b32 v13, v25, v12, 30
	v_ffbh_u32_e32 v25, v27
	v_min_u32_e32 v25, 32, v25
	v_alignbit_b32 v11, v12, v11, 30
	v_xor_b32_e32 v13, v13, v32
	v_sub_u32_e32 v26, 31, v25
	v_xor_b32_e32 v11, v11, v32
	v_alignbit_b32 v27, v27, v13, v26
	v_alignbit_b32 v11, v13, v11, v26
	v_alignbit_b32 v12, v27, v11, 9
	v_ffbh_u32_e32 v13, v12
	v_min_u32_e32 v13, 32, v13
	v_lshrrev_b32_e32 v30, 29, v15
	v_not_b32_e32 v26, v13
	v_alignbit_b32 v11, v12, v11, v26
	v_lshlrev_b32_e32 v12, 31, v30
	v_or_b32_e32 v26, 0x33000000, v12
	v_add_lshl_u32 v13, v13, v25, 23
	v_lshrrev_b32_e32 v11, 9, v11
	v_sub_u32_e32 v13, v26, v13
	v_or_b32_e32 v12, 0.5, v12
	v_lshlrev_b32_e32 v25, 23, v25
	v_or_b32_e32 v11, v13, v11
	v_lshrrev_b32_e32 v13, 9, v27
	v_sub_u32_e32 v12, v12, v25
	v_or_b32_e32 v12, v13, v12
	v_mul_f32_e32 v13, 0x3fc90fda, v12
	s_mov_b32 s8, 0x3fc90fda
	v_fma_f32 v25, v12, s8, -v13
	v_fmac_f32_e32 v25, 0x33a22168, v12
	v_fmac_f32_e32 v25, 0x3fc90fda, v11
	v_lshrrev_b32_e32 v12, 30, v15
	v_add_f32_e32 v11, v13, v25
	v_add_u32_e32 v12, v31, v12

; #define HY_LDF(dst, e) do { const u16* ap_ = rcp + 16 * (e); union { bf16x8 v; uint2 h2[2]; } av_; av_.h2[0] = *(const uint2*)ap_; av_.h2[1] = *(const uint2*)(ap_ + 4); dst = av_.v; } while (0)
; #define layer launder_s(layer_)
; __device__ __forceinline__ void hyena_task(const Params& p, int layer, int c, bool isctx, unsigned char* smem) {
;     ...
;     int nKs = Ls >> 5;
;     const int ngrp = isctx ? 1 : 2;
;     const bool mactive = !isctx || wave < 2;
;     int tt = lane & 15, kg = lane >> 4;
;     int bb = tt & 7;
;     float hb = p.in[32][(layer * 2 + o) * 512 + c];
;     if (mactive)
;     for (int grp = 0; grp < ngrp; grp++) {
;       int mi0 = (wave * ngrp + grp) * 8;
;       f32x4 acc[8];
; #pragma unroll
;       for (int i = 0; i < 8; i++) { acc[i][0] = 0.f; acc[i][1] = 0.f; acc[i][2] = 0.f; acc[i][3] = 0.f; }
;       const u16* rcp = RC + (tt & 3) * HY_CS + (Ls - 16 * mi0 + 8 * kg - 4 * (tt >> 2));
;       const u16* ytp = YT + bb * HY_YS + 8 * kg;
;       bf16x8 ring[8];
;     ...
; #pragma unroll
;       for (int e = -7; e <= -2; e++) HY_LDF(ring[e & 7], e);
;       for (int ks4 = 0; ks4 < nKs; ks4 += 4) {
; #pragma unroll
;         for (int u = 0; u < 4; u++) {
;           const int ks = ks4 + u;
;           bf16x8 bfr = *(const bf16x8*)(ytp + 32 * ks);
;           HY_LDF(ring[(2 * u - 1) & 7], 2 * ks - 1);
;           HY_LDF(ring[(2 * u) & 7], 2 * ks);
; #pragma unroll
;           for (int i = 0; i < 8; i++)
;             acc[i] = __builtin_amdgcn_mfma_f32_16x16x32_bf16(ring[(2 * u - i) & 7], bfr, acc[i], 0, 0, 0);
;         }
;       }
.LBB0_533:
	s_or_b64 exec, exec, s[6:7]
	s_waitcnt lgkmcnt(0)
	s_barrier
	s_mov_b64 s[6:7], exec
	v_readlane_b32 s4, v255, 25
	v_readlane_b32 s5, v255, 26
	s_and_b64 s[4:5], s[6:7], s[4:5]
	s_mov_b64 exec, s[4:5]
	s_cbranch_execz .LBB0_492
	s_and_b64 s[4:5], s[50:51], exec
	s_mov_b32 s4, 0x8100
	s_cselect_b32 s4, s4, 0x10180
	s_add_i32 s4, s4, 0
	v_lshl_add_u32 v33, v132, 1, s4
	v_lshl_add_u32 v32, v131, 1, v33
	ds_read2_b64 v[4:7], v134 offset0:36 offset1:37
	ds_read2_b64 v[8:11], v134 offset0:40 offset1:41
	ds_read2_b64 v[12:15], v134 offset0:44 offset1:45
	ds_read2_b64 v[16:19], v134 offset0:48 offset1:49
	ds_read2_b64 v[20:23], v134 offset0:52 offset1:53
	ds_read2_b64 v[24:27], v134 offset0:56 offset1:57
	ds_read_b128 v[28:31], v32
	ds_read2_b64 v[0:3], v134 offset0:60 offset1:61
	ds_read2_b64 v[34:37], v134 offset0:64 offset1:65
	v_readlane_b32 s4, v255, 27
	s_waitcnt lgkmcnt(0)
	v_mfma_f32_16x16x32_bf16 v[46:49], v[24:27], v[28:31], 0
	v_readlane_b32 s5, v255, 28
	v_mfma_f32_16x16x32_bf16 v[38:41], v[34:37], v[28:31], 0
	v_mfma_f32_16x16x32_bf16 v[42:45], v[0:3], v[28:31], 0
	v_mfma_f32_16x16x32_bf16 v[50:53], v[20:23], v[28:31], 0
	v_mfma_f32_16x16x32_bf16 v[54:57], v[16:19], v[28:31], 0
	v_mfma_f32_16x16x32_bf16 v[58:61], v[12:15], v[28:31], 0
	v_mfma_f32_16x16x32_bf16 v[8:11], v[8:11], v[28:31], 0
	v_mfma_f32_16x16x32_bf16 v[4:7], v[4:7], v[28:31], 0
	ds_read_b128 v[28:31], v32 offset:64
	ds_read2_b64 v[62:65], v134 offset0:68 offset1:69
	s_waitcnt vmcnt(0)
	ds_read2_b64 v[104:107], v134 offset0:72 offset1:73
	s_waitcnt lgkmcnt(0)
	v_mfma_f32_16x16x32_bf16 v[38:41], v[104:107], v[28:31], v[38:41]
	v_mfma_f32_16x16x32_bf16 v[42:45], v[62:65], v[28:31], v[42:45]
	v_mfma_f32_16x16x32_bf16 v[46:49], v[34:37], v[28:31], v[46:49]
	v_mfma_f32_16x16x32_bf16 v[50:53], v[0:3], v[28:31], v[50:53]
	v_mfma_f32_16x16x32_bf16 v[54:57], v[24:27], v[28:31], v[54:57]
	v_mfma_f32_16x16x32_bf16 v[58:61], v[20:23], v[28:31], v[58:61]
	v_mfma_f32_16x16x32_bf16 v[8:11], v[16:19], v[28:31], v[8:11]
	v_mfma_f32_16x16x32_bf16 v[4:7], v[12:15], v[28:31], v[4:7]
	ds_read_b128 v[12:15], v32 offset:128
	ds_read2_b64 v[16:19], v134 offset0:76 offset1:77
	ds_read2_b64 v[28:31], v134 offset0:80 offset1:81
	s_waitcnt lgkmcnt(0)
	v_mfma_f32_16x16x32_bf16 v[38:41], v[28:31], v[12:15], v[38:41]
	v_mfma_f32_16x16x32_bf16 v[42:45], v[16:19], v[12:15], v[42:45]
	v_mfma_f32_16x16x32_bf16 v[46:49], v[104:107], v[12:15], v[46:49]
	v_mfma_f32_16x16x32_bf16 v[50:53], v[62:65], v[12:15], v[50:53]
	v_mfma_f32_16x16x32_bf16 v[54:57], v[34:37], v[12:15], v[54:57]
	v_mfma_f32_16x16x32_bf16 v[58:61], v[0:3], v[12:15], v[58:61]
	v_mfma_f32_16x16x32_bf16 v[8:11], v[24:27], v[12:15], v[8:11]
	v_mfma_f32_16x16x32_bf16 v[4:7], v[20:23], v[12:15], v[4:7]
	ds_read_b128 v[12:15], v32 offset:192
	ds_read2_b64 v[20:23], v134 offset0:84 offset1:85
	ds_read2_b64 v[24:27], v134 offset0:88 offset1:89
	s_waitcnt lgkmcnt(2)
	v_mfma_f32_16x16x32_bf16 v[8:11], v[34:37], v[12:15], v[8:11]
	v_mfma_f32_16x16x32_bf16 v[0:3], v[0:3], v[12:15], v[4:7]
	s_nop 2
	ds_read_b128 v[4:7], v32 offset:256
	ds_read2_b64 v[34:37], v134 offset0:92 offset1:93
	ds_read2_b64 v[108:111], v134 offset0:96 offset1:97
	s_waitcnt lgkmcnt(3)
	v_mfma_f32_16x16x32_bf16 v[38:41], v[24:27], v[12:15], v[38:41]
	v_mfma_f32_16x16x32_bf16 v[42:45], v[20:23], v[12:15], v[42:45]
	v_mfma_f32_16x16x32_bf16 v[46:49], v[28:31], v[12:15], v[46:49]
	v_mfma_f32_16x16x32_bf16 v[50:53], v[16:19], v[12:15], v[50:53]
	v_mfma_f32_16x16x32_bf16 v[54:57], v[104:107], v[12:15], v[54:57]
	v_mfma_f32_16x16x32_bf16 v[58:61], v[62:65], v[12:15], v[58:61]
	s_waitcnt lgkmcnt(0)
	v_mfma_f32_16x16x32_bf16 v[12:15], v[108:111], v[4:7], v[38:41]
	v_mfma_f32_16x16x32_bf16 v[38:41], v[34:37], v[4:7], v[42:45]
	v_mfma_f32_16x16x32_bf16 v[42:45], v[24:27], v[4:7], v[46:49]
	v_mfma_f32_16x16x32_bf16 v[46:49], v[20:23], v[4:7], v[50:53]
	v_mfma_f32_16x16x32_bf16 v[50:53], v[28:31], v[4:7], v[54:57]
	v_mfma_f32_16x16x32_bf16 v[54:57], v[16:19], v[4:7], v[58:61]
	v_mfma_f32_16x16x32_bf16 v[8:11], v[104:107], v[4:7], v[8:11]
	v_mfma_f32_16x16x32_bf16 v[0:3], v[62:65], v[4:7], v[0:3]
	ds_read_b128 v[4:7], v32 offset:320
	ds_read2_b64 v[58:61], v134 offset0:100 offset1:101
	ds_read2_b64 v[62:65], v134 offset0:104 offset1:105
	s_waitcnt lgkmcnt(0)
	v_mfma_f32_16x16x32_bf16 v[12:15], v[62:65], v[4:7], v[12:15]
	v_mfma_f32_16x16x32_bf16 v[38:41], v[58:61], v[4:7], v[38:41]
	v_mfma_f32_16x16x32_bf16 v[42:45], v[108:111], v[4:7], v[42:45]
	v_mfma_f32_16x16x32_bf16 v[46:49], v[34:37], v[4:7], v[46:49]
	v_mfma_f32_16x16x32_bf16 v[50:53], v[24:27], v[4:7], v[50:53]
	v_mfma_f32_16x16x32_bf16 v[54:57], v[20:23], v[4:7], v[54:57]
	v_mfma_f32_16x16x32_bf16 v[8:11], v[28:31], v[4:7], v[8:11]
	v_mfma_f32_16x16x32_bf16 v[0:3], v[16:19], v[4:7], v[0:3]
	ds_read_b128 v[4:7], v32 offset:384
	ds_read2_b64 v[16:19], v134 offset0:108 offset1:109
	ds_read2_b64 v[104:107], v134 offset0:112 offset1:113
	s_waitcnt lgkmcnt(0)
	v_mfma_f32_16x16x32_bf16 v[12:15], v[104:107], v[4:7], v[12:15]
	v_mfma_f32_16x16x32_bf16 v[38:41], v[16:19], v[4:7], v[38:41]
	v_mfma_f32_16x16x32_bf16 v[42:45], v[62:65], v[4:7], v[42:45]
	v_mfma_f32_16x16x32_bf16 v[46:49], v[58:61], v[4:7], v[46:49]
	v_mfma_f32_16x16x32_bf16 v[50:53], v[108:111], v[4:7], v[50:53]
	v_mfma_f32_16x16x32_bf16 v[54:57], v[34:37], v[4:7], v[54:57]
	v_mfma_f32_16x16x32_bf16 v[112:115], v[24:27], v[4:7], v[8:11]
	v_mfma_f32_16x16x32_bf16 v[0:3], v[20:23], v[4:7], v[0:3]
	ds_read_b128 v[116:119], v32 offset:448
	ds_read2_b64 v[4:7], v134 offset0:116 offset1:117
	ds_read2_b64 v[8:11], v134 offset0:120 offset1:121
	s_waitcnt lgkmcnt(0)
	v_mfma_f32_16x16x32_bf16 v[28:31], v[8:11], v[116:119], v[12:15]
	v_mfma_f32_16x16x32_bf16 v[24:27], v[4:7], v[116:119], v[38:41]
	v_mfma_f32_16x16x32_bf16 v[20:23], v[104:107], v[116:119], v[42:45]
	v_mfma_f32_16x16x32_bf16 v[16:19], v[16:19], v[116:119], v[46:49]
	v_mfma_f32_16x16x32_bf16 v[12:15], v[62:65], v[116:119], v[50:53]
	v_mfma_f32_16x16x32_bf16 v[8:11], v[58:61], v[116:119], v[54:57]
	v_mfma_f32_16x16x32_bf16 v[4:7], v[108:111], v[116:119], v[112:115]
	v_mfma_f32_16x16x32_bf16 v[0:3], v[34:37], v[116:119], v[0:3]
	s_and_b64 exec, exec, s[4:5]
	s_cbranch_execz .LBB0_492
; __device__ __forceinline__ u16 f2bf(float f) { unsigned r; asm("v_cvt_pk_bf16_f32 %0, %1, %1" : "=v"(r) : "v"(f)); return (u16)r; }
; __device__ __forceinline__ unsigned pack2(float a, float b) { unsigned r; asm("v_cvt_pk_bf16_f32 %0, %1, %2" : "=v"(r) : "v"(a), "v"(b)); return r; }
; __device__ __forceinline__ void hyena_task(const Params& p, int layer, int c, bool isctx, unsigned char* smem) {
;     ...
;       if (tt < 8) {
;         size_t rowoff = (size_t)rowbase + (size_t)bb * Ls;
; #pragma unroll
;         for (int i = 0; i < 8; i++) {
;           int t0 = 16 * (mi0 + i) + 4 * kg;
;           uint2 gq = *(const uint2*)(GT + bb * HY_YS + t0);
;           uint2 yv = *(const uint2*)(YT + bb * HY_YS + t0);
;           float r0 = __uint_as_float(gq.x << 16) * (acc[i][0] + hb * __uint_as_float(yv.x << 16));
;           float r1 = __uint_as_float(gq.x & 0xffff0000u) * (acc[i][1] + hb * __uint_as_float(yv.x & 0xffff0000u));
;           float r2 = __uint_as_float(gq.y << 16) * (acc[i][2] + hb * __uint_as_float(yv.y << 16));
;           float r3 = __uint_as_float(gq.y & 0xffff0000u) * (acc[i][3] + hb * __uint_as_float(yv.y & 0xffff0000u));
;           if (o == 0) {
;             uint2 ov; ov.x = pack2(r0, r1); ov.y = pack2(r2, r3);
;             *(uint2*)(YB + bb * HY_YS + t0) = ov;
;           } else {
;             u16* YS = (u16*)(p.ws + O_YS) + (rowoff + t0) * 1536 + 1024 + c;
;             YS[0] = f2bf(r0); YS[1536] = f2bf(r1); YS[2 * 1536] = f2bf(r2); YS[3 * 1536] = f2bf(r3);
;           }
	v_mov_b64_e32 v[34:35], s[28:29]
	global_load_dwordx2 v[34:35], v[34:35], off offset:256
	v_readlane_b32 s4, v255, 14
	v_readlane_b32 s5, v255, 15
	v_readlane_b32 s5, v255, 29
	s_add_i32 s4, s5, s4
	s_ashr_i32 s5, s4, 31
	v_lshl_add_u32 v33, v68, 1, v33
	ds_read_b64 v[36:37], v33
	s_mov_b64 s[22:23], -1
	s_and_b64 vcc, exec, s[40:41]
	s_waitcnt lgkmcnt(0)
	v_lshlrev_b32_e32 v39, 16, v36
	v_and_b32_e32 v36, 0xffff0000, v36
	s_waitcnt vmcnt(0)
	v_lshl_add_u64 v[34:35], s[4:5], 2, v[34:35]
	global_load_dword v32, v[34:35], off
	ds_read_b64 v[34:35], v133
	s_waitcnt lgkmcnt(0)
	v_lshlrev_b32_e32 v38, 16, v34
	v_and_b32_e32 v34, 0xffff0000, v34
	s_waitcnt vmcnt(0)
	v_fma_f32 v29, v32, v36, v29
	v_lshlrev_b32_e32 v36, 16, v37
	v_mul_f32_e32 v29, v29, v34
	v_lshlrev_b32_e32 v34, 16, v35
	v_fma_f32 v30, v32, v36, v30
	v_mul_f32_e32 v30, v30, v34
	v_and_b32_e32 v34, 0xffff0000, v35
	v_and_b32_e32 v35, 0xffff0000, v37
	v_fma_f32 v28, v32, v39, v28
	v_fmac_f32_e32 v31, v32, v35
	v_mul_f32_e32 v28, v28, v38
	v_mul_f32_e32 v31, v31, v34
	s_cbranch_vccz .LBB0_537
	v_subrev_co_u32_e32 v34, vcc, 0xce0c000, v76
	s_nop 1
	v_subbrev_co_u32_e32 v35, vcc, 0, v77, vcc
	v_cvt_pk_bf16_f32 v40, v28, v28
	s_mov_b64 s[22:23], 0
	s_waitcnt lgkmcnt(0)
	v_lshl_add_u64 v[34:35], v[34:35], 0, v[72:73]
	v_lshl_add_u64 v[34:35], s[26:27], 1, v[34:35]
	v_add_co_u32_e32 v38, vcc, 0x1700c000, v34
	v_lshl_add_u64 v[36:37], v[34:35], 0, s[86:87]
	s_nop 0
	v_addc_co_u32_e32 v39, vcc, 0, v35, vcc
	v_add_co_u32_e32 v34, vcc, 0x1700e000, v34
	global_store_short v[38:39], v40, off offset:2048
	v_cvt_pk_bf16_f32 v38, v29, v29
	global_store_short v[36:37], v38, off offset:3072
	v_cvt_pk_bf16_f32 v36, v30, v30
	v_addc_co_u32_e32 v35, vcc, 0, v35, vcc
	global_store_short v[34:35], v36, off
	v_cvt_pk_bf16_f32 v36, v31, v31
	global_store_short v[34:35], v36, off offset:3072

; __device__ __forceinline__ u16 f2bf(float f) { unsigned r; asm("v_cvt_pk_bf16_f32 %0, %1, %1" : "=v"(r) : "v"(f)); return (u16)r; }
; __device__ __forceinline__ unsigned pack2(float a, float b) { unsigned r; asm("v_cvt_pk_bf16_f32 %0, %1, %2" : "=v"(r) : "v"(a), "v"(b)); return r; }
; __device__ __forceinline__ void hyena_task(const Params& p, int layer, int c, bool isctx, unsigned char* smem) {
;     ...
;         for (int i = 0; i < 8; i++) {
;           int t0 = 16 * (mi0 + i) + 4 * kg;
;           uint2 gq = *(const uint2*)(GT + bb * HY_YS + t0);
;           uint2 yv = *(const uint2*)(YT + bb * HY_YS + t0);
;           float r0 = __uint_as_float(gq.x << 16) * (acc[i][0] + hb * __uint_as_float(yv.x << 16));
;           float r1 = __uint_as_float(gq.x & 0xffff0000u) * (acc[i][1] + hb * __uint_as_float(yv.x & 0xffff0000u));
;           float r2 = __uint_as_float(gq.y << 16) * (acc[i][2] + hb * __uint_as_float(yv.y << 16));
;           float r3 = __uint_as_float(gq.y & 0xffff0000u) * (acc[i][3] + hb * __uint_as_float(yv.y & 0xffff0000u));
;           if (o == 0) {
;             uint2 ov; ov.x = pack2(r0, r1); ov.y = pack2(r2, r3);
;             *(uint2*)(YB + bb * HY_YS + t0) = ov;
;           } else {
;             u16* YS = (u16*)(p.ws + O_YS) + (rowoff + t0) * 1536 + 1024 + c;
;             YS[0] = f2bf(r0); YS[1536] = f2bf(r1); YS[2 * 1536] = f2bf(r2); YS[3 * 1536] = f2bf(r3);
;           }
.LBB0_539:
	ds_read_b64 v[28:29], v133 offset:32
	ds_read_b64 v[30:31], v33 offset:32
	s_andn2_b64 vcc, exec, s[40:41]
	s_mov_b64 s[4:5], -1
	s_waitcnt lgkmcnt(0)
	v_lshlrev_b32_e32 v34, 16, v28
	v_lshlrev_b32_e32 v35, 16, v30
	v_and_b32_e32 v30, 0xffff0000, v30
	v_and_b32_e32 v28, 0xffff0000, v28
	v_fma_f32 v25, v32, v30, v25
	v_lshlrev_b32_e32 v30, 16, v31
	v_mul_f32_e32 v25, v25, v28
	v_lshlrev_b32_e32 v28, 16, v29
	v_fma_f32 v26, v32, v30, v26
	v_mul_f32_e32 v26, v26, v28
	v_and_b32_e32 v28, 0xffff0000, v29
	v_and_b32_e32 v29, 0xffff0000, v31
	v_fmac_f32_e32 v27, v32, v29
	v_fma_f32 v24, v32, v35, v24
	v_mul_f32_e32 v27, v27, v28
	v_cndmask_b32_e64 v28, 0, 1, s[40:41]
	v_mul_f32_e32 v24, v24, v34
	v_cmp_ne_u32_e64 s[22:23], 1, v28
	s_cbranch_vccnz .LBB0_541
	v_subrev_co_u32_e32 v28, vcc, 0xce0c000, v76
	s_nop 1
	v_subbrev_co_u32_e32 v29, vcc, 0, v77, vcc
	v_cvt_pk_bf16_f32 v36, v24, v24
	s_mov_b64 s[4:5], 0
	s_waitcnt lgkmcnt(0)
	v_lshl_add_u64 v[28:29], v[28:29], 0, v[74:75]
	v_lshl_add_u64 v[28:29], s[26:27], 1, v[28:29]
	v_add_co_u32_e32 v34, vcc, 0x1700c000, v28
	v_lshl_add_u64 v[30:31], v[28:29], 0, s[86:87]
	s_nop 0
	v_addc_co_u32_e32 v35, vcc, 0, v29, vcc
	v_add_co_u32_e32 v28, vcc, 0x1700e000, v28
	global_store_short v[34:35], v36, off offset:2048
	v_cvt_pk_bf16_f32 v34, v25, v25
	global_store_short v[30:31], v34, off offset:3072
	v_cvt_pk_bf16_f32 v30, v26, v26
	v_addc_co_u32_e32 v29, vcc, 0, v29, vcc
	global_store_short v[28:29], v30, off
	v_cvt_pk_bf16_f32 v30, v27, v27
	global_store_short v[28:29], v30, off offset:3072

; __device__ __forceinline__ u16 f2bf(float f) { unsigned r; asm("v_cvt_pk_bf16_f32 %0, %1, %1" : "=v"(r) : "v"(f)); return (u16)r; }
; __device__ __forceinline__ unsigned pack2(float a, float b) { unsigned r; asm("v_cvt_pk_bf16_f32 %0, %1, %2" : "=v"(r) : "v"(a), "v"(b)); return r; }
; __device__ __forceinline__ void hyena_task(const Params& p, int layer, int c, bool isctx, unsigned char* smem) {
;     ...
;         for (int i = 0; i < 8; i++) {
;           int t0 = 16 * (mi0 + i) + 4 * kg;
;           uint2 gq = *(const uint2*)(GT + bb * HY_YS + t0);
;           uint2 yv = *(const uint2*)(YT + bb * HY_YS + t0);
;           float r0 = __uint_as_float(gq.x << 16) * (acc[i][0] + hb * __uint_as_float(yv.x << 16));
;           float r1 = __uint_as_float(gq.x & 0xffff0000u) * (acc[i][1] + hb * __uint_as_float(yv.x & 0xffff0000u));
;           float r2 = __uint_as_float(gq.y << 16) * (acc[i][2] + hb * __uint_as_float(yv.y << 16));
;           float r3 = __uint_as_float(gq.y & 0xffff0000u) * (acc[i][3] + hb * __uint_as_float(yv.y & 0xffff0000u));
;           if (o == 0) {
;             uint2 ov; ov.x = pack2(r0, r1); ov.y = pack2(r2, r3);
;             *(uint2*)(YB + bb * HY_YS + t0) = ov;
;           } else {
;             u16* YS = (u16*)(p.ws + O_YS) + (rowoff + t0) * 1536 + 1024 + c;
;             YS[0] = f2bf(r0); YS[1536] = f2bf(r1); YS[2 * 1536] = f2bf(r2); YS[3 * 1536] = f2bf(r3);
;           }
.LBB0_543:
	ds_read_b64 v[24:25], v133 offset:64
	ds_read_b64 v[26:27], v33 offset:64
	s_and_b64 vcc, exec, s[22:23]
	s_mov_b64 s[4:5], -1
	s_waitcnt lgkmcnt(0)
	v_lshlrev_b32_e32 v28, 16, v24
	v_lshlrev_b32_e32 v29, 16, v26
	v_and_b32_e32 v26, 0xffff0000, v26
	v_and_b32_e32 v24, 0xffff0000, v24
	v_fma_f32 v21, v32, v26, v21
	v_lshlrev_b32_e32 v26, 16, v27
	v_mul_f32_e32 v21, v21, v24
	v_lshlrev_b32_e32 v24, 16, v25
	v_fma_f32 v22, v32, v26, v22
	v_mul_f32_e32 v22, v22, v24
	v_and_b32_e32 v24, 0xffff0000, v25
	v_and_b32_e32 v25, 0xffff0000, v27
	v_fma_f32 v20, v32, v29, v20
	v_fmac_f32_e32 v23, v32, v25
	v_mul_f32_e32 v20, v20, v28
	v_mul_f32_e32 v23, v23, v24
	s_cbranch_vccnz .LBB0_545
	v_subrev_co_u32_e32 v24, vcc, 0xce0c000, v76
	s_nop 1
	v_subbrev_co_u32_e32 v25, vcc, 0, v77, vcc
	v_cvt_pk_bf16_f32 v30, v20, v20
	s_mov_b64 s[4:5], 0
	s_waitcnt lgkmcnt(0)
	v_lshl_add_u64 v[24:25], v[24:25], 0, v[88:89]
	v_lshl_add_u64 v[24:25], s[26:27], 1, v[24:25]
	v_add_co_u32_e32 v28, vcc, 0x1700c000, v24
	v_lshl_add_u64 v[26:27], v[24:25], 0, s[86:87]
	s_nop 0
	v_addc_co_u32_e32 v29, vcc, 0, v25, vcc
	v_add_co_u32_e32 v24, vcc, 0x1700e000, v24
	global_store_short v[28:29], v30, off offset:2048
	v_cvt_pk_bf16_f32 v28, v21, v21
	global_store_short v[26:27], v28, off offset:3072
	v_cvt_pk_bf16_f32 v26, v22, v22
	v_addc_co_u32_e32 v25, vcc, 0, v25, vcc
	global_store_short v[24:25], v26, off
	v_cvt_pk_bf16_f32 v26, v23, v23
	global_store_short v[24:25], v26, off offset:3072

; __device__ __forceinline__ u16 f2bf(float f) { unsigned r; asm("v_cvt_pk_bf16_f32 %0, %1, %1" : "=v"(r) : "v"(f)); return (u16)r; }
; __device__ __forceinline__ unsigned pack2(float a, float b) { unsigned r; asm("v_cvt_pk_bf16_f32 %0, %1, %2" : "=v"(r) : "v"(a), "v"(b)); return r; }
; __device__ __forceinline__ void hyena_task(const Params& p, int layer, int c, bool isctx, unsigned char* smem) {
;     ...
;         for (int i = 0; i < 8; i++) {
;           int t0 = 16 * (mi0 + i) + 4 * kg;
;           uint2 gq = *(const uint2*)(GT + bb * HY_YS + t0);
;           uint2 yv = *(const uint2*)(YT + bb * HY_YS + t0);
;           float r0 = __uint_as_float(gq.x << 16) * (acc[i][0] + hb * __uint_as_float(yv.x << 16));
;           float r1 = __uint_as_float(gq.x & 0xffff0000u) * (acc[i][1] + hb * __uint_as_float(yv.x & 0xffff0000u));
;           float r2 = __uint_as_float(gq.y << 16) * (acc[i][2] + hb * __uint_as_float(yv.y << 16));
;           float r3 = __uint_as_float(gq.y & 0xffff0000u) * (acc[i][3] + hb * __uint_as_float(yv.y & 0xffff0000u));
;           if (o == 0) {
;             uint2 ov; ov.x = pack2(r0, r1); ov.y = pack2(r2, r3);
;             *(uint2*)(YB + bb * HY_YS + t0) = ov;
;           } else {
;             u16* YS = (u16*)(p.ws + O_YS) + (rowoff + t0) * 1536 + 1024 + c;
;             YS[0] = f2bf(r0); YS[1536] = f2bf(r1); YS[2 * 1536] = f2bf(r2); YS[3 * 1536] = f2bf(r3);
;           }
.LBB0_547:
	ds_read_b64 v[20:21], v133 offset:96
	ds_read_b64 v[22:23], v33 offset:96
	s_and_b64 vcc, exec, s[22:23]
	s_mov_b64 s[4:5], -1
	s_waitcnt lgkmcnt(0)
	v_lshlrev_b32_e32 v24, 16, v20
	v_lshlrev_b32_e32 v25, 16, v22
	v_and_b32_e32 v22, 0xffff0000, v22
	v_and_b32_e32 v20, 0xffff0000, v20
	v_fma_f32 v17, v32, v22, v17
	v_lshlrev_b32_e32 v22, 16, v23
	v_mul_f32_e32 v17, v17, v20
	v_lshlrev_b32_e32 v20, 16, v21
	v_fma_f32 v18, v32, v22, v18
	v_mul_f32_e32 v18, v18, v20
	v_and_b32_e32 v20, 0xffff0000, v21
	v_and_b32_e32 v21, 0xffff0000, v23
	v_fma_f32 v16, v32, v25, v16
	v_fmac_f32_e32 v19, v32, v21
	v_mul_f32_e32 v16, v16, v24
	v_mul_f32_e32 v19, v19, v20
	s_cbranch_vccnz .LBB0_549
	v_subrev_co_u32_e32 v20, vcc, 0xce0c000, v76
	s_nop 1
	v_subbrev_co_u32_e32 v21, vcc, 0, v77, vcc
	v_cvt_pk_bf16_f32 v26, v16, v16
	s_mov_b64 s[4:5], 0
	s_waitcnt lgkmcnt(0)
	v_lshl_add_u64 v[20:21], v[20:21], 0, v[90:91]
	v_lshl_add_u64 v[20:21], s[26:27], 1, v[20:21]
	v_add_co_u32_e32 v24, vcc, 0x1700c000, v20
	v_lshl_add_u64 v[22:23], v[20:21], 0, s[86:87]
	s_nop 0
	v_addc_co_u32_e32 v25, vcc, 0, v21, vcc
	v_add_co_u32_e32 v20, vcc, 0x1700e000, v20
	global_store_short v[24:25], v26, off offset:2048
	v_cvt_pk_bf16_f32 v24, v17, v17
	global_store_short v[22:23], v24, off offset:3072
	v_cvt_pk_bf16_f32 v22, v18, v18
	v_addc_co_u32_e32 v21, vcc, 0, v21, vcc
	global_store_short v[20:21], v22, off
	v_cvt_pk_bf16_f32 v22, v19, v19
	global_store_short v[20:21], v22, off offset:3072

; __device__ __forceinline__ u16 f2bf(float f) { unsigned r; asm("v_cvt_pk_bf16_f32 %0, %1, %1" : "=v"(r) : "v"(f)); return (u16)r; }
; __device__ __forceinline__ unsigned pack2(float a, float b) { unsigned r; asm("v_cvt_pk_bf16_f32 %0, %1, %2" : "=v"(r) : "v"(a), "v"(b)); return r; }
; __device__ __forceinline__ void hyena_task(const Params& p, int layer, int c, bool isctx, unsigned char* smem) {
;     ...
;         for (int i = 0; i < 8; i++) {
;           int t0 = 16 * (mi0 + i) + 4 * kg;
;           uint2 gq = *(const uint2*)(GT + bb * HY_YS + t0);
;           uint2 yv = *(const uint2*)(YT + bb * HY_YS + t0);
;           float r0 = __uint_as_float(gq.x << 16) * (acc[i][0] + hb * __uint_as_float(yv.x << 16));
;           float r1 = __uint_as_float(gq.x & 0xffff0000u) * (acc[i][1] + hb * __uint_as_float(yv.x & 0xffff0000u));
;           float r2 = __uint_as_float(gq.y << 16) * (acc[i][2] + hb * __uint_as_float(yv.y << 16));
;           float r3 = __uint_as_float(gq.y & 0xffff0000u) * (acc[i][3] + hb * __uint_as_float(yv.y & 0xffff0000u));
;           if (o == 0) {
;             uint2 ov; ov.x = pack2(r0, r1); ov.y = pack2(r2, r3);
;             *(uint2*)(YB + bb * HY_YS + t0) = ov;
;           } else {
;             u16* YS = (u16*)(p.ws + O_YS) + (rowoff + t0) * 1536 + 1024 + c;
;             YS[0] = f2bf(r0); YS[1536] = f2bf(r1); YS[2 * 1536] = f2bf(r2); YS[3 * 1536] = f2bf(r3);
;           }
.LBB0_551:
	ds_read_b64 v[16:17], v133 offset:128
	ds_read_b64 v[18:19], v33 offset:128
	s_and_b64 vcc, exec, s[22:23]
	s_mov_b64 s[4:5], -1
	s_waitcnt lgkmcnt(0)
	v_lshlrev_b32_e32 v20, 16, v16
	v_lshlrev_b32_e32 v21, 16, v18
	v_and_b32_e32 v18, 0xffff0000, v18
	v_and_b32_e32 v16, 0xffff0000, v16
	v_fma_f32 v13, v32, v18, v13
	v_lshlrev_b32_e32 v18, 16, v19
	v_mul_f32_e32 v13, v13, v16
	v_lshlrev_b32_e32 v16, 16, v17
	v_fma_f32 v14, v32, v18, v14
	v_mul_f32_e32 v14, v14, v16
	v_and_b32_e32 v16, 0xffff0000, v17
	v_and_b32_e32 v17, 0xffff0000, v19
	v_fma_f32 v12, v32, v21, v12
	v_fmac_f32_e32 v15, v32, v17
	v_mul_f32_e32 v12, v12, v20
	v_mul_f32_e32 v15, v15, v16
	s_cbranch_vccnz .LBB0_553
	v_subrev_co_u32_e32 v16, vcc, 0xce0c000, v76
	s_nop 1
	v_subbrev_co_u32_e32 v17, vcc, 0, v77, vcc
	v_cvt_pk_bf16_f32 v22, v12, v12
	s_mov_b64 s[4:5], 0
	s_waitcnt lgkmcnt(0)
	v_lshl_add_u64 v[16:17], v[16:17], 0, v[92:93]
	v_lshl_add_u64 v[16:17], s[26:27], 1, v[16:17]
	v_add_co_u32_e32 v20, vcc, 0x1700c000, v16
	v_lshl_add_u64 v[18:19], v[16:17], 0, s[86:87]
	s_nop 0
	v_addc_co_u32_e32 v21, vcc, 0, v17, vcc
	v_add_co_u32_e32 v16, vcc, 0x1700e000, v16
	global_store_short v[20:21], v22, off offset:2048
	v_cvt_pk_bf16_f32 v20, v13, v13
	global_store_short v[18:19], v20, off offset:3072
	v_cvt_pk_bf16_f32 v18, v14, v14
	v_addc_co_u32_e32 v17, vcc, 0, v17, vcc
	global_store_short v[16:17], v18, off
	v_cvt_pk_bf16_f32 v18, v15, v15
	global_store_short v[16:17], v18, off offset:3072

; __device__ __forceinline__ u16 f2bf(float f) { unsigned r; asm("v_cvt_pk_bf16_f32 %0, %1, %1" : "=v"(r) : "v"(f)); return (u16)r; }
; __device__ __forceinline__ unsigned pack2(float a, float b) { unsigned r; asm("v_cvt_pk_bf16_f32 %0, %1, %2" : "=v"(r) : "v"(a), "v"(b)); return r; }
; __device__ __forceinline__ void hyena_task(const Params& p, int layer, int c, bool isctx, unsigned char* smem) {
;     ...
;         for (int i = 0; i < 8; i++) {
;           int t0 = 16 * (mi0 + i) + 4 * kg;
;           uint2 gq = *(const uint2*)(GT + bb * HY_YS + t0);
;           uint2 yv = *(const uint2*)(YT + bb * HY_YS + t0);
;           float r0 = __uint_as_float(gq.x << 16) * (acc[i][0] + hb * __uint_as_float(yv.x << 16));
;           float r1 = __uint_as_float(gq.x & 0xffff0000u) * (acc[i][1] + hb * __uint_as_float(yv.x & 0xffff0000u));
;           float r2 = __uint_as_float(gq.y << 16) * (acc[i][2] + hb * __uint_as_float(yv.y << 16));
;           float r3 = __uint_as_float(gq.y & 0xffff0000u) * (acc[i][3] + hb * __uint_as_float(yv.y & 0xffff0000u));
;           if (o == 0) {
;             uint2 ov; ov.x = pack2(r0, r1); ov.y = pack2(r2, r3);
;             *(uint2*)(YB + bb * HY_YS + t0) = ov;
;           } else {
;             u16* YS = (u16*)(p.ws + O_YS) + (rowoff + t0) * 1536 + 1024 + c;
;             YS[0] = f2bf(r0); YS[1536] = f2bf(r1); YS[2 * 1536] = f2bf(r2); YS[3 * 1536] = f2bf(r3);
;           }
.LBB0_555:
	ds_read_b64 v[12:13], v133 offset:160
	ds_read_b64 v[14:15], v33 offset:160
	s_and_b64 vcc, exec, s[22:23]
	s_mov_b64 s[4:5], -1
	s_waitcnt lgkmcnt(0)
	v_lshlrev_b32_e32 v16, 16, v12
	v_lshlrev_b32_e32 v17, 16, v14
	v_and_b32_e32 v14, 0xffff0000, v14
	v_and_b32_e32 v12, 0xffff0000, v12
	v_fma_f32 v9, v32, v14, v9
	v_lshlrev_b32_e32 v14, 16, v15
	v_mul_f32_e32 v9, v9, v12
	v_lshlrev_b32_e32 v12, 16, v13
	v_fma_f32 v10, v32, v14, v10
	v_mul_f32_e32 v10, v10, v12
	v_and_b32_e32 v12, 0xffff0000, v13
	v_and_b32_e32 v13, 0xffff0000, v15
	v_fma_f32 v8, v32, v17, v8
	v_fmac_f32_e32 v11, v32, v13
	v_mul_f32_e32 v8, v8, v16
	v_mul_f32_e32 v11, v11, v12
	s_cbranch_vccnz .LBB0_557
	v_subrev_co_u32_e32 v12, vcc, 0xce0c000, v76
	s_nop 1
	v_subbrev_co_u32_e32 v13, vcc, 0, v77, vcc
	v_cvt_pk_bf16_f32 v18, v8, v8
	s_mov_b64 s[4:5], 0
	s_waitcnt lgkmcnt(0)
	v_lshl_add_u64 v[12:13], v[12:13], 0, v[94:95]
	v_lshl_add_u64 v[12:13], s[26:27], 1, v[12:13]
	v_add_co_u32_e32 v16, vcc, 0x1700c000, v12
	v_lshl_add_u64 v[14:15], v[12:13], 0, s[86:87]
	s_nop 0
	v_addc_co_u32_e32 v17, vcc, 0, v13, vcc
	v_add_co_u32_e32 v12, vcc, 0x1700e000, v12
	global_store_short v[16:17], v18, off offset:2048
	v_cvt_pk_bf16_f32 v16, v9, v9
	global_store_short v[14:15], v16, off offset:3072
	v_cvt_pk_bf16_f32 v14, v10, v10
	v_addc_co_u32_e32 v13, vcc, 0, v13, vcc
	global_store_short v[12:13], v14, off
	v_cvt_pk_bf16_f32 v14, v11, v11
	global_store_short v[12:13], v14, off offset:3072

; __device__ __forceinline__ u16 f2bf(float f) { unsigned r; asm("v_cvt_pk_bf16_f32 %0, %1, %1" : "=v"(r) : "v"(f)); return (u16)r; }
; __device__ __forceinline__ unsigned pack2(float a, float b) { unsigned r; asm("v_cvt_pk_bf16_f32 %0, %1, %2" : "=v"(r) : "v"(a), "v"(b)); return r; }
; __device__ __forceinline__ void hyena_task(const Params& p, int layer, int c, bool isctx, unsigned char* smem) {
;     ...
;         for (int i = 0; i < 8; i++) {
;           int t0 = 16 * (mi0 + i) + 4 * kg;
;           uint2 gq = *(const uint2*)(GT + bb * HY_YS + t0);
;           uint2 yv = *(const uint2*)(YT + bb * HY_YS + t0);
;           float r0 = __uint_as_float(gq.x << 16) * (acc[i][0] + hb * __uint_as_float(yv.x << 16));
;           float r1 = __uint_as_float(gq.x & 0xffff0000u) * (acc[i][1] + hb * __uint_as_float(yv.x & 0xffff0000u));
;           float r2 = __uint_as_float(gq.y << 16) * (acc[i][2] + hb * __uint_as_float(yv.y << 16));
;           float r3 = __uint_as_float(gq.y & 0xffff0000u) * (acc[i][3] + hb * __uint_as_float(yv.y & 0xffff0000u));
;           if (o == 0) {
;             uint2 ov; ov.x = pack2(r0, r1); ov.y = pack2(r2, r3);
;             *(uint2*)(YB + bb * HY_YS + t0) = ov;
;           } else {
;             u16* YS = (u16*)(p.ws + O_YS) + (rowoff + t0) * 1536 + 1024 + c;
;             YS[0] = f2bf(r0); YS[1536] = f2bf(r1); YS[2 * 1536] = f2bf(r2); YS[3 * 1536] = f2bf(r3);
;           }
.LBB0_559:
	ds_read_b64 v[8:9], v133 offset:192
	ds_read_b64 v[10:11], v33 offset:192
	s_and_b64 vcc, exec, s[22:23]
	s_mov_b64 s[4:5], -1
	s_waitcnt lgkmcnt(0)
	v_lshlrev_b32_e32 v12, 16, v8
	v_lshlrev_b32_e32 v13, 16, v10
	v_and_b32_e32 v10, 0xffff0000, v10
	v_and_b32_e32 v8, 0xffff0000, v8
	v_fma_f32 v5, v32, v10, v5
	v_lshlrev_b32_e32 v10, 16, v11
	v_mul_f32_e32 v5, v5, v8
	v_lshlrev_b32_e32 v8, 16, v9
	v_fma_f32 v6, v32, v10, v6
	v_mul_f32_e32 v6, v6, v8
	v_and_b32_e32 v8, 0xffff0000, v9
	v_and_b32_e32 v9, 0xffff0000, v11
	v_fma_f32 v4, v32, v13, v4
	v_fmac_f32_e32 v7, v32, v9
	v_mul_f32_e32 v4, v4, v12
	v_mul_f32_e32 v7, v7, v8
	s_cbranch_vccnz .LBB0_561
	v_subrev_co_u32_e32 v8, vcc, 0xce0c000, v76
	s_nop 1
	v_subbrev_co_u32_e32 v9, vcc, 0, v77, vcc
	v_cvt_pk_bf16_f32 v14, v4, v4
	s_mov_b64 s[4:5], 0
	s_waitcnt lgkmcnt(0)
	v_lshl_add_u64 v[8:9], v[8:9], 0, v[96:97]
	v_lshl_add_u64 v[8:9], s[26:27], 1, v[8:9]
	v_add_co_u32_e32 v12, vcc, 0x1700c000, v8
	v_lshl_add_u64 v[10:11], v[8:9], 0, s[86:87]
	s_nop 0
	v_addc_co_u32_e32 v13, vcc, 0, v9, vcc
	v_add_co_u32_e32 v8, vcc, 0x1700e000, v8
	global_store_short v[12:13], v14, off offset:2048
	v_cvt_pk_bf16_f32 v12, v5, v5
	global_store_short v[10:11], v12, off offset:3072
	v_cvt_pk_bf16_f32 v10, v6, v6
	v_addc_co_u32_e32 v9, vcc, 0, v9, vcc
	global_store_short v[8:9], v10, off
	v_cvt_pk_bf16_f32 v10, v7, v7
	global_store_short v[8:9], v10, off offset:3072

; __device__ __forceinline__ u16 f2bf(float f) { unsigned r; asm("v_cvt_pk_bf16_f32 %0, %1, %1" : "=v"(r) : "v"(f)); return (u16)r; }
; __device__ __forceinline__ unsigned pack2(float a, float b) { unsigned r; asm("v_cvt_pk_bf16_f32 %0, %1, %2" : "=v"(r) : "v"(a), "v"(b)); return r; }
; __device__ __forceinline__ void hyena_task(const Params& p, int layer, int c, bool isctx, unsigned char* smem) {
;     ...
;         for (int i = 0; i < 8; i++) {
;           int t0 = 16 * (mi0 + i) + 4 * kg;
;           uint2 gq = *(const uint2*)(GT + bb * HY_YS + t0);
;           uint2 yv = *(const uint2*)(YT + bb * HY_YS + t0);
;           float r0 = __uint_as_float(gq.x << 16) * (acc[i][0] + hb * __uint_as_float(yv.x << 16));
;           float r1 = __uint_as_float(gq.x & 0xffff0000u) * (acc[i][1] + hb * __uint_as_float(yv.x & 0xffff0000u));
;           float r2 = __uint_as_float(gq.y << 16) * (acc[i][2] + hb * __uint_as_float(yv.y << 16));
;           float r3 = __uint_as_float(gq.y & 0xffff0000u) * (acc[i][3] + hb * __uint_as_float(yv.y & 0xffff0000u));
;           if (o == 0) {
;             uint2 ov; ov.x = pack2(r0, r1); ov.y = pack2(r2, r3);
;             *(uint2*)(YB + bb * HY_YS + t0) = ov;
;           } else {
;             u16* YS = (u16*)(p.ws + O_YS) + (rowoff + t0) * 1536 + 1024 + c;
;             YS[0] = f2bf(r0); YS[1536] = f2bf(r1); YS[2 * 1536] = f2bf(r2); YS[3 * 1536] = f2bf(r3);
;           }
.LBB0_563:
	ds_read_b64 v[4:5], v133 offset:224
	ds_read_b64 v[6:7], v33 offset:224
	s_and_b64 vcc, exec, s[22:23]
	s_mov_b64 s[4:5], -1
	s_waitcnt lgkmcnt(0)
	v_lshlrev_b32_e32 v8, 16, v4
	v_lshlrev_b32_e32 v9, 16, v6
	v_and_b32_e32 v6, 0xffff0000, v6
	v_and_b32_e32 v4, 0xffff0000, v4
	v_fma_f32 v1, v32, v6, v1
	v_lshlrev_b32_e32 v6, 16, v7
	v_mul_f32_e32 v1, v1, v4
	v_lshlrev_b32_e32 v4, 16, v5
	v_fma_f32 v2, v32, v6, v2
	v_mul_f32_e32 v2, v2, v4
	v_and_b32_e32 v4, 0xffff0000, v5
	v_and_b32_e32 v5, 0xffff0000, v7
	v_fma_f32 v0, v32, v9, v0
	v_fmac_f32_e32 v3, v32, v5
	v_mul_f32_e32 v0, v0, v8
	v_mul_f32_e32 v3, v3, v4
	s_cbranch_vccnz .LBB0_565
	v_subrev_co_u32_e32 v4, vcc, 0xce0c000, v76
	s_nop 1
	v_subbrev_co_u32_e32 v5, vcc, 0, v77, vcc
	v_cvt_pk_bf16_f32 v10, v0, v0
	s_mov_b64 s[4:5], 0
	s_waitcnt lgkmcnt(0)
	v_lshl_add_u64 v[4:5], v[4:5], 0, v[98:99]
	v_lshl_add_u64 v[4:5], s[26:27], 1, v[4:5]
	v_add_co_u32_e32 v8, vcc, 0x1700c000, v4
	v_lshl_add_u64 v[6:7], v[4:5], 0, s[86:87]
	s_nop 0
	v_addc_co_u32_e32 v9, vcc, 0, v5, vcc
	v_add_co_u32_e32 v4, vcc, 0x1700e000, v4
	global_store_short v[8:9], v10, off offset:2048
	v_cvt_pk_bf16_f32 v8, v1, v1
	global_store_short v[6:7], v8, off offset:3072
	v_cvt_pk_bf16_f32 v6, v2, v2
	v_addc_co_u32_e32 v5, vcc, 0, v5, vcc
	global_store_short v[4:5], v6, off
	v_cvt_pk_bf16_f32 v6, v3, v3
	global_store_short v[4:5], v6, off offset:3072
